# scan producer trimmed: decay factors by prefix products and one reciprocal (20 instead of 32 transcendentals per chunk), kd via one fma with a precomputed 1-ka
# baseline (speedup 1.0000x reference)
.LBB0_59:
	v_readlane_b32 s10, v241, 22
	v_readlane_b32 s11, v241, 23
	v_or_b32_e32 v66, s37, v14
	v_lshlrev_b32_e32 v66, 2, v66
	s_and_b64 s[16:17], s[42:43], exec
	s_mov_b32 s12, 0x10000
	s_cselect_b32 s12, s12, 0xffff0000
	s_movk_i32 s13, 0x400
	s_cselect_b32 s13, s13, 0xfffffc00
	s_cselect_b32 s4, 0, 0x2000000
	s_add_u32 s28, s30, 0xaaf0000
	s_addc_u32 s29, s31, 0
	s_add_u32 s28, s28, s4
	s_addc_u32 s29, s29, 0
	s_add_u32 s34, s28, 0x4000000
	s_addc_u32 s35, s29, 0
	s_add_u32 s8, s30, 0x19af0000
	s_addc_u32 s9, s31, 0
	s_add_u32 s14, s30, 0x17af0000
	s_addc_u32 s15, s31, 0
	global_load_dwordx4 v[106:109], v66, s[10:11]
	v_lshlrev_b32_e32 v67, 2, v61
	v_sub_u32_e32 v68, 0x1fff, v67
	v_cndmask_b32_e64 v67, v68, v67, s[42:43]
	v_add_u32_e32 v67, s80, v67
	v_lshlrev_b32_e32 v67, 10, v67
	v_or_b32_e32 v68, s37, v14
	v_lshl_add_u32 v110, v68, 1, v67
	s_lshl_b32 s5, s64, 4
	s_add_i32 s5, s5, s37
	v_add_u32_e32 v68, s5, v15
	v_lshl_add_u32 v114, v68, 1, v67
	v_add_u32_e32 v111, s13, v110
	v_add_u32_e32 v115, s13, v114
	v_add_u32_e32 v112, s13, v111
	v_add_u32_e32 v116, s13, v115
	v_add_u32_e32 v113, s13, v112
	v_add_u32_e32 v117, s13, v116
	v_lshlrev_b32_e32 v119, 12, v61
	v_lshl_or_b32 v119, v15, 4, v119
	v_lshlrev_b32_e32 v123, 8, v61
	v_lshl_or_b32 v123, v15, 4, v123
	v_add_u32_e32 v123, 0x22000, v123
	global_load_dwordx2 v[16:17], v110, s[44:45]
	global_load_dwordx2 v[18:19], v110, s[46:47]
	global_load_dwordx2 v[20:21], v110, s[8:9]
	global_load_dwordx2 v[22:23], v110, s[34:35]
	global_load_dwordx2 v[24:25], v110, s[28:29]
	global_load_ushort v26, v114, s[14:15]
	global_load_dwordx2 v[28:29], v111, s[44:45]
	global_load_dwordx2 v[30:31], v111, s[46:47]
	global_load_dwordx2 v[32:33], v111, s[8:9]
	global_load_dwordx2 v[34:35], v111, s[34:35]
	global_load_dwordx2 v[36:37], v111, s[28:29]
	global_load_ushort v38, v115, s[14:15]
	global_load_dwordx2 v[40:41], v112, s[44:45]
	global_load_dwordx2 v[42:43], v112, s[46:47]
	global_load_dwordx2 v[44:45], v112, s[8:9]
	global_load_dwordx2 v[46:47], v112, s[34:35]
	global_load_dwordx2 v[48:49], v112, s[28:29]
	global_load_ushort v50, v116, s[14:15]
	global_load_dwordx2 v[52:53], v113, s[44:45]
	global_load_dwordx2 v[54:55], v113, s[46:47]
	global_load_dwordx2 v[56:57], v113, s[8:9]
	global_load_dwordx2 v[58:59], v113, s[34:35]
	global_load_dwordx2 v[60:61], v113, s[28:29]
	global_load_ushort v62, v117, s[14:15]
	v_add_u32_e32 v110, s12, v110
	v_add_u32_e32 v114, s12, v114
	v_add_u32_e32 v111, s12, v111
	v_add_u32_e32 v115, s12, v115
	v_add_u32_e32 v112, s12, v112
	v_add_u32_e32 v116, s12, v116
	v_add_u32_e32 v113, s12, v113
	v_add_u32_e32 v117, s12, v117
	s_waitcnt vmcnt(0)
	v_pk_add_f32 v[172:173], v[106:107], 1.0 op_sel_hi:[1,0] neg_lo:[1,0] neg_hi:[1,0]
	v_pk_add_f32 v[174:175], v[108:109], 1.0 op_sel_hi:[1,0] neg_lo:[1,0] neg_hi:[1,0]
	v_cvt_f32_f16_e32 v124, v24
	v_cvt_f32_f16_sdwa v125, v24 dst_sel:DWORD dst_unused:UNUSED_PAD src0_sel:WORD_1
	v_cvt_f32_f16_e32 v126, v25
	v_cvt_f32_f16_sdwa v127, v25 dst_sel:DWORD dst_unused:UNUSED_PAD src0_sel:WORD_1
	v_cvt_f32_f16_e32 v128, v36
	v_cvt_f32_f16_sdwa v129, v36 dst_sel:DWORD dst_unused:UNUSED_PAD src0_sel:WORD_1
	v_cvt_f32_f16_e32 v130, v37
	v_cvt_f32_f16_sdwa v131, v37 dst_sel:DWORD dst_unused:UNUSED_PAD src0_sel:WORD_1
	v_cvt_f32_f16_e32 v132, v48
	v_cvt_f32_f16_sdwa v133, v48 dst_sel:DWORD dst_unused:UNUSED_PAD src0_sel:WORD_1
	v_cvt_f32_f16_e32 v134, v49
	v_cvt_f32_f16_sdwa v135, v49 dst_sel:DWORD dst_unused:UNUSED_PAD src0_sel:WORD_1
	v_cvt_f32_f16_e32 v136, v60
	v_cvt_f32_f16_sdwa v137, v60 dst_sel:DWORD dst_unused:UNUSED_PAD src0_sel:WORD_1
	v_cvt_f32_f16_e32 v138, v61
	v_cvt_f32_f16_sdwa v139, v61 dst_sel:DWORD dst_unused:UNUSED_PAD src0_sel:WORD_1
	v_exp_f32_e64 v124, -v124
	v_exp_f32_e64 v125, -v125
	v_exp_f32_e64 v126, -v126
	v_exp_f32_e64 v127, -v127
	v_exp_f32_e64 v128, -v128
	v_exp_f32_e64 v129, -v129
	v_exp_f32_e64 v130, -v130
	v_exp_f32_e64 v131, -v131
	v_exp_f32_e64 v132, -v132
	v_exp_f32_e64 v133, -v133
	v_exp_f32_e64 v134, -v134
	v_exp_f32_e64 v135, -v135
	v_exp_f32_e64 v136, -v136
	v_exp_f32_e64 v137, -v137
	v_exp_f32_e64 v138, -v138
	v_exp_f32_e64 v139, -v139
	v_mov_b64_e32 v[140:141], v[124:125]
	v_mov_b64_e32 v[142:143], v[126:127]
	v_pk_mul_f32 v[144:145], v[140:141], v[128:129]
	v_pk_mul_f32 v[146:147], v[142:143], v[130:131]
	v_pk_mul_f32 v[148:149], v[144:145], v[132:133]
	v_pk_mul_f32 v[150:151], v[146:147], v[134:135]
	v_pk_mul_f32 v[152:153], v[148:149], v[136:137]
	v_pk_mul_f32 v[154:155], v[150:151], v[138:139]
	v_rcp_f32_e32 v168, v152
	v_rcp_f32_e32 v169, v153
	v_rcp_f32_e32 v170, v154
	v_rcp_f32_e32 v171, v155
	s_nop 0
	v_pk_mul_f32 v[164:165], v[168:169], v[136:137]
	v_pk_mul_f32 v[166:167], v[170:171], v[138:139]
	v_pk_mul_f32 v[160:161], v[164:165], v[132:133]
	v_pk_mul_f32 v[162:163], v[166:167], v[134:135]
	v_pk_mul_f32 v[156:157], v[160:161], v[128:129]
	v_pk_mul_f32 v[158:159], v[162:163], v[130:131]
	v_cvt_f32_f16_e32 v68, v22
	v_cvt_f32_f16_sdwa v69, v22 dst_sel:DWORD dst_unused:UNUSED_PAD src0_sel:WORD_1
	v_cvt_f32_f16_e32 v70, v23
	v_cvt_f32_f16_sdwa v71, v23 dst_sel:DWORD dst_unused:UNUSED_PAD src0_sel:WORD_1
	v_lshlrev_b32_e32 v72, 16, v20
	v_and_b32_e32 v73, 0xffff0000, v20
	v_lshlrev_b32_e32 v74, 16, v21
	v_and_b32_e32 v75, 0xffff0000, v21
	v_lshlrev_b32_e32 v76, 16, v18
	v_and_b32_e32 v77, 0xffff0000, v18
	v_lshlrev_b32_e32 v78, 16, v19
	v_and_b32_e32 v79, 0xffff0000, v19
	v_lshlrev_b32_e32 v80, 16, v16
	v_and_b32_e32 v81, 0xffff0000, v16
	v_lshlrev_b32_e32 v82, 16, v17
	v_and_b32_e32 v83, 0xffff0000, v17
	v_pk_mul_f32 v[84:85], v[72:73], v[68:69]
	v_pk_mul_f32 v[86:87], v[74:75], v[70:71]
	v_pk_fma_f32 v[88:89], v[106:107], v[68:69], v[172:173]
	v_pk_fma_f32 v[90:91], v[108:109], v[70:71], v[174:175]
	v_pk_mul_f32 v[84:85], v[84:85], v[156:157]
	v_pk_mul_f32 v[86:87], v[86:87], v[158:159]
	v_pk_mul_f32 v[88:89], v[88:89], v[76:77]
	v_pk_mul_f32 v[90:91], v[90:91], v[78:79]
	ds_write_b128 v119, v[84:87] offset:512
	v_pk_mul_f32 v[88:89], v[88:89], v[156:157]
	v_pk_mul_f32 v[90:91], v[90:91], v[158:159]
	v_pk_mul_f32 v[80:81], v[80:81], v[140:141]
	v_pk_mul_f32 v[82:83], v[82:83], v[142:143]
	ds_write_b128 v119, v[88:91] offset:768
	v_lshlrev_b32_e32 v96, 16, v26
	v_cvt_pk_f16_f32 v92, v72, v73
	v_cvt_pk_f16_f32 v93, v74, v75
	v_cvt_pk_f16_f32 v94, v80, v81
	v_cvt_pk_f16_f32 v95, v82, v83
	ds_write_b128 v119, v[92:95] offset:256
	v_cvt_f32_f16_e32 v68, v34
	v_cvt_f32_f16_sdwa v69, v34 dst_sel:DWORD dst_unused:UNUSED_PAD src0_sel:WORD_1
	v_cvt_f32_f16_e32 v70, v35
	v_cvt_f32_f16_sdwa v71, v35 dst_sel:DWORD dst_unused:UNUSED_PAD src0_sel:WORD_1
	v_lshlrev_b32_e32 v72, 16, v32
	v_and_b32_e32 v73, 0xffff0000, v32
	v_lshlrev_b32_e32 v74, 16, v33
	v_and_b32_e32 v75, 0xffff0000, v33
	v_lshlrev_b32_e32 v76, 16, v30
	v_and_b32_e32 v77, 0xffff0000, v30
	v_lshlrev_b32_e32 v78, 16, v31
	v_and_b32_e32 v79, 0xffff0000, v31
	v_lshlrev_b32_e32 v80, 16, v28
	v_and_b32_e32 v81, 0xffff0000, v28
	v_lshlrev_b32_e32 v82, 16, v29
	v_and_b32_e32 v83, 0xffff0000, v29
	v_pk_mul_f32 v[84:85], v[72:73], v[68:69]
	v_pk_mul_f32 v[86:87], v[74:75], v[70:71]
	v_pk_fma_f32 v[88:89], v[106:107], v[68:69], v[172:173]
	v_pk_fma_f32 v[90:91], v[108:109], v[70:71], v[174:175]
	v_pk_mul_f32 v[84:85], v[84:85], v[160:161]
	v_pk_mul_f32 v[86:87], v[86:87], v[162:163]
	v_pk_mul_f32 v[88:89], v[88:89], v[76:77]
	v_pk_mul_f32 v[90:91], v[90:91], v[78:79]
	ds_write_b128 v119, v[84:87] offset:1536
	v_pk_mul_f32 v[88:89], v[88:89], v[160:161]
	v_pk_mul_f32 v[90:91], v[90:91], v[162:163]
	v_pk_mul_f32 v[72:73], v[72:73], v[140:141]
	v_pk_mul_f32 v[74:75], v[74:75], v[142:143]
	v_pk_mul_f32 v[80:81], v[80:81], v[144:145]
	v_pk_mul_f32 v[82:83], v[82:83], v[146:147]
	ds_write_b128 v119, v[88:91] offset:1792
	v_lshlrev_b32_e32 v97, 16, v38
	v_cvt_pk_f16_f32 v92, v72, v73
	v_cvt_pk_f16_f32 v93, v74, v75
	v_cvt_pk_f16_f32 v94, v80, v81
	v_cvt_pk_f16_f32 v95, v82, v83
	ds_write_b128 v119, v[92:95] offset:1280
	v_cvt_f32_f16_e32 v68, v46
	v_cvt_f32_f16_sdwa v69, v46 dst_sel:DWORD dst_unused:UNUSED_PAD src0_sel:WORD_1
	v_cvt_f32_f16_e32 v70, v47
	v_cvt_f32_f16_sdwa v71, v47 dst_sel:DWORD dst_unused:UNUSED_PAD src0_sel:WORD_1
	v_lshlrev_b32_e32 v72, 16, v44
	v_and_b32_e32 v73, 0xffff0000, v44
	v_lshlrev_b32_e32 v74, 16, v45
	v_and_b32_e32 v75, 0xffff0000, v45
	v_lshlrev_b32_e32 v76, 16, v42
	v_and_b32_e32 v77, 0xffff0000, v42
	v_lshlrev_b32_e32 v78, 16, v43
	v_and_b32_e32 v79, 0xffff0000, v43
	v_lshlrev_b32_e32 v80, 16, v40
	v_and_b32_e32 v81, 0xffff0000, v40
	v_lshlrev_b32_e32 v82, 16, v41
	v_and_b32_e32 v83, 0xffff0000, v41
	v_pk_mul_f32 v[84:85], v[72:73], v[68:69]
	v_pk_mul_f32 v[86:87], v[74:75], v[70:71]
	v_pk_fma_f32 v[88:89], v[106:107], v[68:69], v[172:173]
	v_pk_fma_f32 v[90:91], v[108:109], v[70:71], v[174:175]
	v_pk_mul_f32 v[84:85], v[84:85], v[164:165]
	v_pk_mul_f32 v[86:87], v[86:87], v[166:167]
	v_pk_mul_f32 v[88:89], v[88:89], v[76:77]
	v_pk_mul_f32 v[90:91], v[90:91], v[78:79]
	ds_write_b128 v119, v[84:87] offset:2560
	v_pk_mul_f32 v[88:89], v[88:89], v[164:165]
	v_pk_mul_f32 v[90:91], v[90:91], v[166:167]
	v_pk_mul_f32 v[72:73], v[72:73], v[144:145]
	v_pk_mul_f32 v[74:75], v[74:75], v[146:147]
	v_pk_mul_f32 v[80:81], v[80:81], v[148:149]
	v_pk_mul_f32 v[82:83], v[82:83], v[150:151]
	ds_write_b128 v119, v[88:91] offset:2816
	v_lshlrev_b32_e32 v98, 16, v50
	v_cvt_pk_f16_f32 v92, v72, v73
	v_cvt_pk_f16_f32 v93, v74, v75
	v_cvt_pk_f16_f32 v94, v80, v81
	v_cvt_pk_f16_f32 v95, v82, v83
	ds_write_b128 v119, v[92:95] offset:2304
	v_cvt_f32_f16_e32 v68, v58
	v_cvt_f32_f16_sdwa v69, v58 dst_sel:DWORD dst_unused:UNUSED_PAD src0_sel:WORD_1
	v_cvt_f32_f16_e32 v70, v59
	v_cvt_f32_f16_sdwa v71, v59 dst_sel:DWORD dst_unused:UNUSED_PAD src0_sel:WORD_1
	v_lshlrev_b32_e32 v72, 16, v56
	v_and_b32_e32 v73, 0xffff0000, v56
	v_lshlrev_b32_e32 v74, 16, v57
	v_and_b32_e32 v75, 0xffff0000, v57
	v_lshlrev_b32_e32 v76, 16, v54
	v_and_b32_e32 v77, 0xffff0000, v54
	v_lshlrev_b32_e32 v78, 16, v55
	v_and_b32_e32 v79, 0xffff0000, v55
	v_lshlrev_b32_e32 v80, 16, v52
	v_and_b32_e32 v81, 0xffff0000, v52
	v_lshlrev_b32_e32 v82, 16, v53
	v_and_b32_e32 v83, 0xffff0000, v53
	v_pk_mul_f32 v[84:85], v[72:73], v[68:69]
	v_pk_mul_f32 v[86:87], v[74:75], v[70:71]
	v_pk_fma_f32 v[88:89], v[106:107], v[68:69], v[172:173]
	v_pk_fma_f32 v[90:91], v[108:109], v[70:71], v[174:175]
	v_pk_mul_f32 v[84:85], v[84:85], v[168:169]
	v_pk_mul_f32 v[86:87], v[86:87], v[170:171]
	v_pk_mul_f32 v[88:89], v[88:89], v[76:77]
	v_pk_mul_f32 v[90:91], v[90:91], v[78:79]
	ds_write_b128 v119, v[84:87] offset:3584
	v_pk_mul_f32 v[88:89], v[88:89], v[168:169]
	v_pk_mul_f32 v[90:91], v[90:91], v[170:171]
	v_pk_mul_f32 v[72:73], v[72:73], v[148:149]
	v_pk_mul_f32 v[74:75], v[74:75], v[150:151]
	ds_write_b128 v119, v[88:91] offset:3840
	v_lshlrev_b32_e32 v99, 16, v62
	v_cvt_pk_f16_f32 v92, v72, v73
	v_cvt_pk_f16_f32 v93, v74, v75
	v_cvt_pk_f16_f32 v94, v80, v81
	v_cvt_pk_f16_f32 v95, v82, v83
	ds_write_b128 v119, v[92:95] offset:3328
	ds_write_b128 v119, v[152:155] offset:3072
	ds_write_b128 v123, v[96:99]
	global_load_dwordx2 v[16:17], v110, s[44:45]
	global_load_dwordx2 v[18:19], v110, s[46:47]
	global_load_dwordx2 v[20:21], v110, s[8:9]
	global_load_dwordx2 v[22:23], v110, s[34:35]
	global_load_dwordx2 v[24:25], v110, s[28:29]
	global_load_ushort v26, v114, s[14:15]
	global_load_dwordx2 v[28:29], v111, s[44:45]
	global_load_dwordx2 v[30:31], v111, s[46:47]
	global_load_dwordx2 v[32:33], v111, s[8:9]
	global_load_dwordx2 v[34:35], v111, s[34:35]
	global_load_dwordx2 v[36:37], v111, s[28:29]
	global_load_ushort v38, v115, s[14:15]
	global_load_dwordx2 v[40:41], v112, s[44:45]
	global_load_dwordx2 v[42:43], v112, s[46:47]
	global_load_dwordx2 v[44:45], v112, s[8:9]
	global_load_dwordx2 v[46:47], v112, s[34:35]
	global_load_dwordx2 v[48:49], v112, s[28:29]
	global_load_ushort v50, v116, s[14:15]
	global_load_dwordx2 v[52:53], v113, s[44:45]
	global_load_dwordx2 v[54:55], v113, s[46:47]
	global_load_dwordx2 v[56:57], v113, s[8:9]
	global_load_dwordx2 v[58:59], v113, s[34:35]
	global_load_dwordx2 v[60:61], v113, s[28:29]
	global_load_ushort v62, v117, s[14:15]
	v_add_u32_e32 v110, s12, v110
	v_add_u32_e32 v114, s12, v114
	v_add_u32_e32 v111, s12, v111
	v_add_u32_e32 v115, s12, v115
	v_add_u32_e32 v112, s12, v112
	v_add_u32_e32 v116, s12, v116
	v_add_u32_e32 v113, s12, v113
	v_add_u32_e32 v117, s12, v117
	s_waitcnt lgkmcnt(0)
	s_barrier
	s_mov_b32 s6, 0
.Lprod_loop:
	s_cmp_eq_u32 s6, 0x7f
	s_cbranch_scc1 .Lprod_bar
	s_nop 0
	v_xor_b32_e32 v119, 0x10000, v119
	v_xor_b32_e32 v123, 0x1000, v123
	s_waitcnt vmcnt(0)
	s_nop 0
	v_cvt_f32_f16_e64 v124, v24
	v_cvt_f32_f16_sdwa v125, v24 dst_sel:DWORD dst_unused:UNUSED_PAD src0_sel:WORD_1
	v_cvt_f32_f16_e64 v126, v25
	v_cvt_f32_f16_sdwa v127, v25 dst_sel:DWORD dst_unused:UNUSED_PAD src0_sel:WORD_1
	v_cvt_f32_f16_e64 v128, v36
	v_cvt_f32_f16_sdwa v129, v36 dst_sel:DWORD dst_unused:UNUSED_PAD src0_sel:WORD_1
	v_cvt_f32_f16_e64 v130, v37
	v_cvt_f32_f16_sdwa v131, v37 dst_sel:DWORD dst_unused:UNUSED_PAD src0_sel:WORD_1
	v_cvt_f32_f16_e64 v132, v48
	v_cvt_f32_f16_sdwa v133, v48 dst_sel:DWORD dst_unused:UNUSED_PAD src0_sel:WORD_1
	v_cvt_f32_f16_e64 v134, v49
	v_cvt_f32_f16_sdwa v135, v49 dst_sel:DWORD dst_unused:UNUSED_PAD src0_sel:WORD_1
	v_cvt_f32_f16_e64 v136, v60
	v_cvt_f32_f16_sdwa v137, v60 dst_sel:DWORD dst_unused:UNUSED_PAD src0_sel:WORD_1
	v_cvt_f32_f16_e64 v138, v61
	v_cvt_f32_f16_sdwa v139, v61 dst_sel:DWORD dst_unused:UNUSED_PAD src0_sel:WORD_1
	v_exp_f32_e64 v124, -v124
	v_exp_f32_e64 v125, -v125
	v_exp_f32_e64 v126, -v126
	v_exp_f32_e64 v127, -v127
	v_exp_f32_e64 v128, -v128
	v_exp_f32_e64 v129, -v129
	v_exp_f32_e64 v130, -v130
	v_exp_f32_e64 v131, -v131
	v_exp_f32_e64 v132, -v132
	v_exp_f32_e64 v133, -v133
	v_exp_f32_e64 v134, -v134
	v_exp_f32_e64 v135, -v135
	v_exp_f32_e64 v136, -v136
	v_exp_f32_e64 v137, -v137
	v_exp_f32_e64 v138, -v138
	v_exp_f32_e64 v139, -v139
	v_mov_b64_e64 v[140:141], v[124:125]
	v_mov_b64_e64 v[142:143], v[126:127]
	v_pk_mul_f32 v[144:145], v[140:141], v[128:129]
	v_pk_mul_f32 v[146:147], v[142:143], v[130:131]
	v_pk_mul_f32 v[148:149], v[144:145], v[132:133]
	v_pk_mul_f32 v[150:151], v[146:147], v[134:135]
	v_pk_mul_f32 v[152:153], v[148:149], v[136:137]
	v_pk_mul_f32 v[154:155], v[150:151], v[138:139]
	v_rcp_f32_e64 v168, v152
	v_rcp_f32_e64 v169, v153
	v_rcp_f32_e64 v170, v154
	v_rcp_f32_e64 v171, v155
	s_nop 0
	s_nop 0
	v_pk_mul_f32 v[164:165], v[168:169], v[136:137]
	v_pk_mul_f32 v[166:167], v[170:171], v[138:139]
	v_pk_mul_f32 v[160:161], v[164:165], v[132:133]
	v_pk_mul_f32 v[162:163], v[166:167], v[134:135]
	v_pk_mul_f32 v[156:157], v[160:161], v[128:129]
	v_pk_mul_f32 v[158:159], v[162:163], v[130:131]
	v_cvt_f32_f16_e64 v68, v22
	v_cvt_f32_f16_sdwa v69, v22 dst_sel:DWORD dst_unused:UNUSED_PAD src0_sel:WORD_1
	v_cvt_f32_f16_e64 v70, v23
	v_cvt_f32_f16_sdwa v71, v23 dst_sel:DWORD dst_unused:UNUSED_PAD src0_sel:WORD_1
	v_lshlrev_b32_e64 v72, 16, v20
	v_and_b32_e32 v73, 0xffff0000, v20
	v_lshlrev_b32_e64 v74, 16, v21
	v_and_b32_e32 v75, 0xffff0000, v21
	v_lshlrev_b32_e64 v76, 16, v18
	v_and_b32_e32 v77, 0xffff0000, v18
	v_lshlrev_b32_e64 v78, 16, v19
	v_and_b32_e32 v79, 0xffff0000, v19
	v_lshlrev_b32_e64 v80, 16, v16
	v_and_b32_e32 v81, 0xffff0000, v16
	v_lshlrev_b32_e64 v82, 16, v17
	v_and_b32_e32 v83, 0xffff0000, v17
	v_pk_mul_f32 v[84:85], v[72:73], v[68:69]
	v_pk_mul_f32 v[86:87], v[74:75], v[70:71]
	v_pk_fma_f32 v[88:89], v[106:107], v[68:69], v[172:173]
	v_pk_fma_f32 v[90:91], v[108:109], v[70:71], v[174:175]
	v_pk_mul_f32 v[84:85], v[84:85], v[156:157]
	v_pk_mul_f32 v[86:87], v[86:87], v[158:159]
	v_pk_mul_f32 v[88:89], v[88:89], v[76:77]
	v_pk_mul_f32 v[90:91], v[90:91], v[78:79]
	ds_write_b128 v119, v[84:87] offset:512
	v_pk_mul_f32 v[88:89], v[88:89], v[156:157]
	v_pk_mul_f32 v[90:91], v[90:91], v[158:159]
	v_pk_mul_f32 v[80:81], v[80:81], v[140:141]
	v_pk_mul_f32 v[82:83], v[82:83], v[142:143]
	ds_write_b128 v119, v[88:91] offset:768
	v_lshlrev_b32_e64 v96, 16, v26
	v_cvt_pk_f16_f32 v92, v72, v73
	v_cvt_pk_f16_f32 v93, v74, v75
	v_cvt_pk_f16_f32 v94, v80, v81
	v_cvt_pk_f16_f32 v95, v82, v83
	ds_write_b128 v119, v[92:95] offset:256
	v_cvt_f32_f16_e64 v68, v34
	v_cvt_f32_f16_sdwa v69, v34 dst_sel:DWORD dst_unused:UNUSED_PAD src0_sel:WORD_1
	v_cvt_f32_f16_e64 v70, v35
	v_cvt_f32_f16_sdwa v71, v35 dst_sel:DWORD dst_unused:UNUSED_PAD src0_sel:WORD_1
	v_lshlrev_b32_e64 v72, 16, v32
	v_and_b32_e32 v73, 0xffff0000, v32
	v_lshlrev_b32_e64 v74, 16, v33
	v_and_b32_e32 v75, 0xffff0000, v33
	v_lshlrev_b32_e64 v76, 16, v30
	v_and_b32_e32 v77, 0xffff0000, v30
	v_lshlrev_b32_e64 v78, 16, v31
	v_and_b32_e32 v79, 0xffff0000, v31
	v_lshlrev_b32_e64 v80, 16, v28
	v_and_b32_e32 v81, 0xffff0000, v28
	v_lshlrev_b32_e64 v82, 16, v29
	v_and_b32_e32 v83, 0xffff0000, v29
	v_pk_mul_f32 v[84:85], v[72:73], v[68:69]
	v_pk_mul_f32 v[86:87], v[74:75], v[70:71]
	v_pk_fma_f32 v[88:89], v[106:107], v[68:69], v[172:173]
	v_pk_fma_f32 v[90:91], v[108:109], v[70:71], v[174:175]
	v_pk_mul_f32 v[84:85], v[84:85], v[160:161]
	v_pk_mul_f32 v[86:87], v[86:87], v[162:163]
	v_pk_mul_f32 v[88:89], v[88:89], v[76:77]
	v_pk_mul_f32 v[90:91], v[90:91], v[78:79]
	ds_write_b128 v119, v[84:87] offset:1536
	v_pk_mul_f32 v[88:89], v[88:89], v[160:161]
	v_pk_mul_f32 v[90:91], v[90:91], v[162:163]
	v_pk_mul_f32 v[72:73], v[72:73], v[140:141]
	v_pk_mul_f32 v[74:75], v[74:75], v[142:143]
	v_pk_mul_f32 v[80:81], v[80:81], v[144:145]
	v_pk_mul_f32 v[82:83], v[82:83], v[146:147]
	ds_write_b128 v119, v[88:91] offset:1792
	v_lshlrev_b32_e64 v97, 16, v38
	v_cvt_pk_f16_f32 v92, v72, v73
	v_cvt_pk_f16_f32 v93, v74, v75
	v_cvt_pk_f16_f32 v94, v80, v81
	v_cvt_pk_f16_f32 v95, v82, v83
	ds_write_b128 v119, v[92:95] offset:1280
	v_cvt_f32_f16_e64 v68, v46
	v_cvt_f32_f16_sdwa v69, v46 dst_sel:DWORD dst_unused:UNUSED_PAD src0_sel:WORD_1
	v_cvt_f32_f16_e64 v70, v47
	v_cvt_f32_f16_sdwa v71, v47 dst_sel:DWORD dst_unused:UNUSED_PAD src0_sel:WORD_1
	v_lshlrev_b32_e64 v72, 16, v44
	v_and_b32_e32 v73, 0xffff0000, v44
	v_lshlrev_b32_e64 v74, 16, v45
	v_and_b32_e32 v75, 0xffff0000, v45
	v_lshlrev_b32_e64 v76, 16, v42
	v_and_b32_e32 v77, 0xffff0000, v42
	v_lshlrev_b32_e64 v78, 16, v43
	v_and_b32_e32 v79, 0xffff0000, v43
	v_lshlrev_b32_e64 v80, 16, v40
	v_and_b32_e32 v81, 0xffff0000, v40
	v_lshlrev_b32_e64 v82, 16, v41
	v_and_b32_e32 v83, 0xffff0000, v41
	v_pk_mul_f32 v[84:85], v[72:73], v[68:69]
	v_pk_mul_f32 v[86:87], v[74:75], v[70:71]
	v_pk_fma_f32 v[88:89], v[106:107], v[68:69], v[172:173]
	v_pk_fma_f32 v[90:91], v[108:109], v[70:71], v[174:175]
	v_pk_mul_f32 v[84:85], v[84:85], v[164:165]
	v_pk_mul_f32 v[86:87], v[86:87], v[166:167]
	v_pk_mul_f32 v[88:89], v[88:89], v[76:77]
	v_pk_mul_f32 v[90:91], v[90:91], v[78:79]
	ds_write_b128 v119, v[84:87] offset:2560
	v_pk_mul_f32 v[88:89], v[88:89], v[164:165]
	v_pk_mul_f32 v[90:91], v[90:91], v[166:167]
	v_pk_mul_f32 v[72:73], v[72:73], v[144:145]
	v_pk_mul_f32 v[74:75], v[74:75], v[146:147]
	v_pk_mul_f32 v[80:81], v[80:81], v[148:149]
	v_pk_mul_f32 v[82:83], v[82:83], v[150:151]
	ds_write_b128 v119, v[88:91] offset:2816
	v_lshlrev_b32_e64 v98, 16, v50
	v_cvt_pk_f16_f32 v92, v72, v73
	v_cvt_pk_f16_f32 v93, v74, v75
	v_cvt_pk_f16_f32 v94, v80, v81
	v_cvt_pk_f16_f32 v95, v82, v83
	ds_write_b128 v119, v[92:95] offset:2304
	v_cvt_f32_f16_e64 v68, v58
	v_cvt_f32_f16_sdwa v69, v58 dst_sel:DWORD dst_unused:UNUSED_PAD src0_sel:WORD_1
	v_cvt_f32_f16_e64 v70, v59
	v_cvt_f32_f16_sdwa v71, v59 dst_sel:DWORD dst_unused:UNUSED_PAD src0_sel:WORD_1
	v_lshlrev_b32_e64 v72, 16, v56
	v_and_b32_e32 v73, 0xffff0000, v56
	v_lshlrev_b32_e64 v74, 16, v57
	v_and_b32_e32 v75, 0xffff0000, v57
	v_lshlrev_b32_e64 v76, 16, v54
	v_and_b32_e32 v77, 0xffff0000, v54
	v_lshlrev_b32_e64 v78, 16, v55
	v_and_b32_e32 v79, 0xffff0000, v55
	v_lshlrev_b32_e64 v80, 16, v52
	v_and_b32_e32 v81, 0xffff0000, v52
	v_lshlrev_b32_e64 v82, 16, v53
	v_and_b32_e32 v83, 0xffff0000, v53
	v_pk_mul_f32 v[84:85], v[72:73], v[68:69]
	v_pk_mul_f32 v[86:87], v[74:75], v[70:71]
	v_pk_fma_f32 v[88:89], v[106:107], v[68:69], v[172:173]
	v_pk_fma_f32 v[90:91], v[108:109], v[70:71], v[174:175]
	v_pk_mul_f32 v[84:85], v[84:85], v[168:169]
	v_pk_mul_f32 v[86:87], v[86:87], v[170:171]
	v_pk_mul_f32 v[88:89], v[88:89], v[76:77]
	v_pk_mul_f32 v[90:91], v[90:91], v[78:79]
	ds_write_b128 v119, v[84:87] offset:3584
	v_pk_mul_f32 v[88:89], v[88:89], v[168:169]
	v_pk_mul_f32 v[90:91], v[90:91], v[170:171]
	v_pk_mul_f32 v[72:73], v[72:73], v[148:149]
	v_pk_mul_f32 v[74:75], v[74:75], v[150:151]
	ds_write_b128 v119, v[88:91] offset:3840
	v_lshlrev_b32_e64 v99, 16, v62
	v_cvt_pk_f16_f32 v92, v72, v73
	v_cvt_pk_f16_f32 v93, v74, v75
	v_cvt_pk_f16_f32 v94, v80, v81
	v_cvt_pk_f16_f32 v95, v82, v83
	ds_write_b128 v119, v[92:95] offset:3328
	ds_write_b128 v119, v[152:155] offset:3072
	ds_write_b128 v123, v[96:99]
	s_cmp_ge_u32 s6, 0x7e
	s_cbranch_scc1 .Lprod_bar
	s_nop 0
	global_load_dwordx2 v[16:17], v110, s[44:45]
	global_load_dwordx2 v[18:19], v110, s[46:47]
	global_load_dwordx2 v[20:21], v110, s[8:9]
	global_load_dwordx2 v[22:23], v110, s[34:35]
	global_load_dwordx2 v[24:25], v110, s[28:29]
	global_load_ushort v26, v114, s[14:15]
	global_load_dwordx2 v[28:29], v111, s[44:45]
	global_load_dwordx2 v[30:31], v111, s[46:47]
	global_load_dwordx2 v[32:33], v111, s[8:9]
	global_load_dwordx2 v[34:35], v111, s[34:35]
	global_load_dwordx2 v[36:37], v111, s[28:29]
	global_load_ushort v38, v115, s[14:15]
	global_load_dwordx2 v[40:41], v112, s[44:45]
	global_load_dwordx2 v[42:43], v112, s[46:47]
	global_load_dwordx2 v[44:45], v112, s[8:9]
	global_load_dwordx2 v[46:47], v112, s[34:35]
	global_load_dwordx2 v[48:49], v112, s[28:29]
	global_load_ushort v50, v116, s[14:15]
	global_load_dwordx2 v[52:53], v113, s[44:45]
	global_load_dwordx2 v[54:55], v113, s[46:47]
	global_load_dwordx2 v[56:57], v113, s[8:9]
	global_load_dwordx2 v[58:59], v113, s[34:35]
	global_load_dwordx2 v[60:61], v113, s[28:29]
	global_load_ushort v62, v117, s[14:15]
	v_add_u32_e64 v110, s12, v110
	v_add_u32_e64 v114, s12, v114
	v_add_u32_e64 v111, s12, v111
	v_add_u32_e64 v115, s12, v115
	v_add_u32_e64 v112, s12, v112
	v_add_u32_e64 v116, s12, v116
	v_add_u32_e64 v113, s12, v113
	v_add_u32_e64 v117, s12, v117
